# LayerNorm row reductions: xor-8/4/2/1 butterfly steps via DPP adds (same pairing/order) instead of ds_bpermute + lgkmcnt(0)
# speedup vs baseline: 1.0077x; 1.0077x over previous
; DI void phase_ln(const P& p, int l) {
;     ...
;     for (int h = 0; h < 2; ++h) {
;       if (h && !two) break;
;       const int rr = h ? rowb : row;
;       float s = 0.f;
; #pragma unroll
;       for (int i = 0; i < 4; ++i) s += (v[h][i].x + v[h][i].y) + (v[h][i].z + v[h][i].w);
; #pragma unroll
;       for (int o = 32; o >= 1; o >>= 1) s += __shfl_xor(s, o);
;       const float mean = s * (1.f / 1024.f);
;       float q = 0.f;
; #pragma unroll
;       for (int i = 0; i < 4; ++i) {
;         v[h][i].x -= mean; v[h][i].y -= mean; v[h][i].z -= mean; v[h][i].w -= mean;
;         q += (v[h][i].x * v[h][i].x + v[h][i].y * v[h][i].y) + (v[h][i].z * v[h][i].z + v[h][i].w * v[h][i].w);
;       }
; #pragma unroll
;       for (int o = 32; o >= 1; o >>= 1) q += __shfl_xor(q, o);
;       const float rstd = rsqrtf(q * (1.f / 1024.f) + 1e-5f);
;       const int mr = rr < MLAT ? (rr >> 11) : 16;
;       const float* md = p.mod + (size_t)(1 * 17 + mr) * 3072;
; #pragma unroll
;       for (int i = 0; i < 4; ++i) {
;         const int col = i * 256 + lane * 4;
;         float4 y;
;         y.x = v[h][i].x * rstd * g4[i].x + b4[i].x;
;         y.y = v[h][i].y * rstd * g4[i].y + b4[i].y;
;         y.z = v[h][i].z * rstd * g4[i].z + b4[i].z;
;         y.w = v[h][i].w * rstd * g4[i].w + b4[i].w;
;         if (l == 1 || rr < MLAT) *(float4*)(p.out + (size_t)rr * 1024 + col) = y;
.Lln_nopf:
	v_add_u32_e32 v63, 1, v62
	v_cmp_lt_i32_e64 s[40:41], v63, v65
	v_lshl_add_u64 v[90:91], v[80:81], 0, v[78:79]
	v_cmp_gt_i32_e32 vcc, s21, v62
	v_cndmask_b32_e64 v86, v62, v63, s[40:41]
	v_ashrrev_i32_e32 v87, 31, v86
	v_lshlrev_b64 v[88:89], 12, v[86:87]
	v_lshl_add_u64 v[38:39], v[66:67], 0, v[88:89]
	global_load_dwordx4 v[34:37], v[38:39], off
	global_load_dwordx4 v[46:49], v[38:39], off offset:1024
	global_load_dwordx4 v[42:45], v[38:39], off offset:2048
	s_nop 0
	global_load_dwordx4 v[38:41], v[38:39], off offset:3072
	s_nop 0
	global_load_dwordx4 v[50:53], v[90:91], off offset:3072
	global_load_dwordx4 v[54:57], v[90:91], off offset:2048
	global_load_dwordx4 v[58:61], v[90:91], off offset:1024
	s_or_b64 s[52:53], s[46:47], vcc
	s_waitcnt vmcnt(1)
	v_mov_b32_e32 v0, v57
	s_waitcnt vmcnt(0)
	v_mov_b32_e32 v92, v58
	v_mov_b32_e32 v93, v60
	v_mov_b32_e32 v98, v59
	v_mov_b32_e32 v99, v61
	v_pk_add_f32 v[92:93], v[92:93], v[98:99]
	v_pk_add_f32 v[94:95], v[56:57], v[0:1]
	v_pk_add_f32 v[98:99], v[92:93], v[92:93] op_sel:[0,1] op_sel_hi:[1,0]
	global_load_dwordx4 v[90:93], v[90:91], off
	v_mov_b32_e32 v0, v55
	v_pk_add_f32 v[96:97], v[54:55], v[0:1]
	v_mov_b32_e32 v95, v53
	v_mov_b32_e32 v97, v52
	v_mov_b32_e32 v99, v51
	v_pk_add_f32 v[94:95], v[96:97], v[94:95]
	s_waitcnt vmcnt(0)
	v_mov_b32_e32 v100, v90
	v_mov_b32_e32 v101, v92
	v_mov_b32_e32 v106, v91
	v_mov_b32_e32 v107, v93
	v_pk_add_f32 v[100:101], v[100:101], v[106:107]
	s_nop 0
	v_add_f32_e32 v0, v100, v101
	v_add_f32_e32 v100, 0, v0
	v_mov_b32_e32 v101, v50
	v_pk_add_f32 v[96:97], v[100:101], v[98:99]
	s_nop 0
	v_pk_add_f32 v[94:95], v[96:97], v[94:95]
	s_nop 0
	v_add_f32_e32 v0, v94, v95
	ds_bpermute_b32 v94, v69, v0
	s_waitcnt lgkmcnt(0)
	v_add_f32_e32 v0, v0, v94
	ds_bpermute_b32 v94, v71, v0
	s_waitcnt lgkmcnt(0)
	v_add_f32_e32 v0, v0, v94
	s_nop 1
	v_add_f32_dpp v0, v0, v0 row_ror:8 row_mask:0xf bank_mask:0xf
	s_nop 1
	v_mov_b32_dpp v94, v0 row_shl:4 row_mask:0xf bank_mask:0x5
	v_mov_b32_dpp v94, v0 row_shr:4 row_mask:0xf bank_mask:0xa
	v_add_f32_e32 v0, v0, v94
	s_nop 1
	v_add_f32_dpp v0, v0, v0 quad_perm:[2,3,0,1] row_mask:0xf bank_mask:0xf
	s_nop 1
	v_add_f32_dpp v0, v0, v0 quad_perm:[1,0,3,2] row_mask:0xf bank_mask:0xf
	v_mul_f32_e32 v0, 0x3a800000, v0
	v_pk_add_f32 v[96:97], v[90:91], v[0:1] op_sel_hi:[1,0] neg_lo:[0,1] neg_hi:[0,1]
	v_pk_add_f32 v[98:99], v[92:93], v[0:1] op_sel_hi:[1,0] neg_lo:[0,1] neg_hi:[0,1]
	v_mov_b32_e32 v92, v97
	v_mov_b32_e32 v93, v99
	v_mov_b32_e32 v90, v96
	v_mov_b32_e32 v91, v98
	v_pk_mul_f32 v[92:93], v[92:93], v[92:93]
	s_nop 0
	v_pk_fma_f32 v[90:91], v[90:91], v[90:91], v[92:93]
	v_pk_add_f32 v[92:93], v[58:59], v[0:1] op_sel_hi:[1,0] neg_lo:[0,1] neg_hi:[0,1]
	v_pk_add_f32 v[94:95], v[90:91], v[90:91] op_sel_hi:[0,1]
	v_pk_add_f32 v[90:91], v[60:61], v[0:1] op_sel_hi:[1,0] neg_lo:[0,1] neg_hi:[0,1]
	v_mov_b32_e32 v60, v93
	v_mov_b32_e32 v61, v91
	v_mov_b32_e32 v58, v92
	v_mov_b32_e32 v59, v90
	v_pk_mul_f32 v[60:61], v[60:61], v[60:61]
	s_nop 0
	v_pk_fma_f32 v[58:59], v[58:59], v[58:59], v[60:61]
	v_pk_add_f32 v[60:61], v[54:55], v[0:1] op_sel_hi:[1,0] neg_lo:[0,1] neg_hi:[0,1]
	v_pk_add_f32 v[100:101], v[58:59], v[58:59] op_sel_hi:[0,1]
	v_pk_add_f32 v[58:59], v[56:57], v[0:1] op_sel_hi:[1,0] neg_lo:[0,1] neg_hi:[0,1]
	v_mul_f32_e32 v54, v60, v60
	v_pk_fma_f32 v[106:107], v[60:61], v[60:61], v[54:55] op_sel_hi:[1,1,0]
	v_mul_f32_e32 v54, v58, v58
	v_pk_fma_f32 v[108:109], v[58:59], v[58:59], v[54:55] op_sel_hi:[1,1,0]
	v_pk_add_f32 v[56:57], v[50:51], v[0:1] op_sel_hi:[1,0] neg_lo:[0,1] neg_hi:[0,1]
	v_pk_add_f32 v[54:55], v[52:53], v[0:1] op_sel_hi:[1,0] neg_lo:[0,1] neg_hi:[0,1]
	v_pk_mul_f32 v[50:51], v[56:57], v[56:57]
	v_pk_mul_f32 v[52:53], v[54:55], v[54:55]
	v_mov_b32_e32 v106, v50
	v_mov_b32_e32 v108, v51
	v_mov_b32_e32 v94, v52
	v_mov_b32_e32 v100, v53
	v_pk_add_f32 v[50:51], v[106:107], v[108:109]
	v_pk_add_f32 v[52:53], v[94:95], v[100:101]
	s_nop 0
	v_pk_add_f32 v[50:51], v[50:51], v[52:53]
	s_nop 0
	v_add_f32_e32 v0, v50, v51
	ds_bpermute_b32 v50, v69, v0
	s_waitcnt lgkmcnt(0)
	v_add_f32_e32 v0, v0, v50
	ds_bpermute_b32 v50, v71, v0
	s_waitcnt lgkmcnt(0)
	v_add_f32_e32 v0, v0, v50
	s_nop 1
	v_add_f32_dpp v0, v0, v0 row_ror:8 row_mask:0xf bank_mask:0xf
	s_nop 1
	v_mov_b32_dpp v50, v0 row_shl:4 row_mask:0xf bank_mask:0x5
	v_mov_b32_dpp v50, v0 row_shr:4 row_mask:0xf bank_mask:0xa
	v_add_f32_e32 v0, v0, v50
	s_nop 1
	v_add_f32_dpp v0, v0, v0 quad_perm:[2,3,0,1] row_mask:0xf bank_mask:0xf
	s_nop 1
	v_add_f32_dpp v0, v0, v0 quad_perm:[1,0,3,2] row_mask:0xf bank_mask:0xf
	v_mov_b32_e32 v50, 0x3727c5ac
	v_fmamk_f32 v0, v0, 0x3a800000, v50
	v_cmp_gt_f32_e32 vcc, s37, v0
	v_mul_f32_e32 v50, 0x4b800000, v0
	s_nop 0
	v_cndmask_b32_e32 v0, v0, v50, vcc
	v_rsq_f32_e32 v0, v0
	s_nop 0
	v_mul_f32_e32 v50, 0x45800000, v0
	v_cndmask_b32_e32 v94, v0, v50, vcc
	v_pk_mul_f32 v[50:51], v[96:97], v[94:95] op_sel_hi:[1,0]
	v_pk_mul_f32 v[52:53], v[98:99], v[94:95] op_sel_hi:[1,0]
	v_pk_fma_f32 v[50:51], v[2:3], v[50:51], v[10:11]
	v_pk_fma_f32 v[52:53], v[4:5], v[52:53], v[12:13]
	v_lshl_add_u64 v[96:97], v[82:83], 0, v[78:79]
	s_and_saveexec_b64 s[42:43], s[52:53]
	s_cbranch_execz .LBB0_34
	global_store_dwordx4 v[96:97], v[50:53], off

; DI void phase_ln(const P& p, int l) {
;     ...
;     for (int h = 0; h < 2; ++h) {
;       if (h && !two) break;
;       const int rr = h ? rowb : row;
;       float s = 0.f;
; #pragma unroll
;       for (int i = 0; i < 4; ++i) s += (v[h][i].x + v[h][i].y) + (v[h][i].z + v[h][i].w);
; #pragma unroll
;       for (int o = 32; o >= 1; o >>= 1) s += __shfl_xor(s, o);
;       const float mean = s * (1.f / 1024.f);
;       float q = 0.f;
; #pragma unroll
;       for (int i = 0; i < 4; ++i) {
;         v[h][i].x -= mean; v[h][i].y -= mean; v[h][i].z -= mean; v[h][i].w -= mean;
;         q += (v[h][i].x * v[h][i].x + v[h][i].y * v[h][i].y) + (v[h][i].z * v[h][i].z + v[h][i].w * v[h][i].w);
;       }
; #pragma unroll
;       for (int o = 32; o >= 1; o >>= 1) q += __shfl_xor(q, o);
;       const float rstd = rsqrtf(q * (1.f / 1024.f) + 1e-5f);
;       const int mr = rr < MLAT ? (rr >> 11) : 16;
;       const float* md = p.mod + (size_t)(1 * 17 + mr) * 3072;
; #pragma unroll
;       for (int i = 0; i < 4; ++i) {
;         const int col = i * 256 + lane * 4;
;         float4 y;
;         y.x = v[h][i].x * rstd * g4[i].x + b4[i].x;
;         y.y = v[h][i].y * rstd * g4[i].y + b4[i].y;
;         y.z = v[h][i].z * rstd * g4[i].z + b4[i].z;
;         y.w = v[h][i].w * rstd * g4[i].w + b4[i].w;
;         if (l == 1 || rr < MLAT) *(float4*)(p.out + (size_t)rr * 1024 + col) = y;
.LBB0_49:
	v_mov_b32_e32 v50, v34
	v_mov_b32_e32 v51, v36
	v_mov_b32_e32 v52, v35
	v_mov_b32_e32 v53, v37
	v_pk_add_f32 v[50:51], v[50:51], v[52:53]
	v_mov_b32_e32 v52, v46
	v_mov_b32_e32 v53, v48
	v_mov_b32_e32 v54, v47
	v_mov_b32_e32 v55, v49
	v_pk_add_f32 v[52:53], v[52:53], v[54:55]
	v_mov_b32_e32 v54, v43
	v_mov_b32_e32 v56, v45
	v_add_f32_e32 v50, v50, v51
	v_pk_add_f32 v[52:53], v[52:53], v[52:53] op_sel:[0,1] op_sel_hi:[1,0]
	v_pk_add_f32 v[54:55], v[42:43], v[54:55]
	v_pk_add_f32 v[56:57], v[44:45], v[56:57]
	v_add_f32_e32 v50, 0, v50
	v_mov_b32_e32 v51, v38
	v_mov_b32_e32 v53, v39
	v_mov_b32_e32 v55, v40
	v_mov_b32_e32 v57, v41
	v_pk_add_f32 v[50:51], v[50:51], v[52:53]
	v_pk_add_f32 v[52:53], v[54:55], v[56:57]
	s_movk_i32 s2, 0x7fff
	v_pk_add_f32 v[50:51], v[50:51], v[52:53]
	v_cmp_gt_i32_e32 vcc, s2, v62
	v_add_f32_e32 v50, v50, v51
	ds_bpermute_b32 v51, v69, v50
	s_or_b64 s[40:41], s[46:47], vcc
	s_waitcnt lgkmcnt(0)
	v_add_f32_e32 v50, v50, v51
	ds_bpermute_b32 v51, v71, v50
	s_waitcnt lgkmcnt(0)
	v_add_f32_e32 v50, v50, v51
	s_nop 1
	v_add_f32_dpp v50, v50, v50 row_ror:8 row_mask:0xf bank_mask:0xf
	s_nop 1
	v_mov_b32_dpp v51, v50 row_shl:4 row_mask:0xf bank_mask:0x5
	v_mov_b32_dpp v51, v50 row_shr:4 row_mask:0xf bank_mask:0xa
	v_add_f32_e32 v50, v50, v51
	s_nop 1
	v_add_f32_dpp v50, v50, v50 quad_perm:[2,3,0,1] row_mask:0xf bank_mask:0xf
	s_nop 1
	v_add_f32_dpp v50, v50, v50 quad_perm:[1,0,3,2] row_mask:0xf bank_mask:0xf
	v_mul_f32_e32 v52, 0x3a800000, v50
	v_pk_add_f32 v[50:51], v[46:47], v[52:53] op_sel_hi:[1,0] neg_lo:[0,1] neg_hi:[0,1]
	v_pk_add_f32 v[48:49], v[48:49], v[52:53] op_sel_hi:[1,0] neg_lo:[0,1] neg_hi:[0,1]
	v_mov_b32_e32 v54, v51
	v_mov_b32_e32 v55, v49
	v_mov_b32_e32 v46, v50
	v_mov_b32_e32 v47, v48
	v_pk_mul_f32 v[54:55], v[54:55], v[54:55]
	v_pk_add_f32 v[44:45], v[44:45], v[52:53] op_sel_hi:[1,0] neg_lo:[0,1] neg_hi:[0,1]
	v_pk_fma_f32 v[46:47], v[46:47], v[46:47], v[54:55]
	v_pk_add_f32 v[36:37], v[36:37], v[52:53] op_sel_hi:[1,0] neg_lo:[0,1] neg_hi:[0,1]
	v_pk_add_f32 v[54:55], v[46:47], v[46:47] op_sel_hi:[0,1]
	v_pk_add_f32 v[46:47], v[42:43], v[52:53] op_sel_hi:[1,0] neg_lo:[0,1] neg_hi:[0,1]
	v_pk_add_f32 v[34:35], v[34:35], v[52:53] op_sel_hi:[1,0] neg_lo:[0,1] neg_hi:[0,1]
	v_mul_f32_e32 v42, v46, v46
	v_pk_fma_f32 v[56:57], v[46:47], v[46:47], v[42:43] op_sel_hi:[1,1,0]
	v_mul_f32_e32 v42, v44, v44
	v_mov_b32_e32 v90, v35
	v_mov_b32_e32 v91, v37
	v_pk_fma_f32 v[58:59], v[44:45], v[44:45], v[42:43] op_sel_hi:[1,1,0]
	v_pk_add_f32 v[42:43], v[38:39], v[52:53] op_sel_hi:[1,0] neg_lo:[0,1] neg_hi:[0,1]
	v_pk_add_f32 v[38:39], v[40:41], v[52:53] op_sel_hi:[1,0] neg_lo:[0,1] neg_hi:[0,1]
	v_mov_b32_e32 v52, v34
	v_mov_b32_e32 v53, v36
	v_pk_mul_f32 v[90:91], v[90:91], v[90:91]
	v_pk_mul_f32 v[40:41], v[42:43], v[42:43]
	v_pk_fma_f32 v[52:53], v[52:53], v[52:53], v[90:91]
	v_pk_mul_f32 v[60:61], v[38:39], v[38:39]
	v_pk_add_f32 v[52:53], v[52:53], v[52:53] op_sel_hi:[0,1]
	v_mov_b32_e32 v56, v40
	v_mov_b32_e32 v58, v41
	v_mov_b32_e32 v52, v60
	v_mov_b32_e32 v54, v61
	v_pk_add_f32 v[40:41], v[56:57], v[58:59]
	v_pk_add_f32 v[52:53], v[52:53], v[54:55]
	s_nop 0
	v_pk_add_f32 v[40:41], v[40:41], v[52:53]
	v_lshl_add_u64 v[52:53], v[74:75], 0, v[88:89]
	v_add_f32_e32 v40, v40, v41
	ds_bpermute_b32 v41, v69, v40
	s_waitcnt lgkmcnt(0)
	v_add_f32_e32 v40, v40, v41
	ds_bpermute_b32 v41, v71, v40
	s_waitcnt lgkmcnt(0)
	v_add_f32_e32 v40, v40, v41
	s_nop 1
	v_add_f32_dpp v40, v40, v40 row_ror:8 row_mask:0xf bank_mask:0xf
	s_nop 1
	v_mov_b32_dpp v41, v40 row_shl:4 row_mask:0xf bank_mask:0x5
	v_mov_b32_dpp v41, v40 row_shr:4 row_mask:0xf bank_mask:0xa
	v_add_f32_e32 v40, v40, v41
	s_nop 1
	v_add_f32_dpp v40, v40, v40 quad_perm:[2,3,0,1] row_mask:0xf bank_mask:0xf
	s_nop 1
	v_add_f32_dpp v40, v40, v40 quad_perm:[1,0,3,2] row_mask:0xf bank_mask:0xf
	v_mov_b32_e32 v41, 0x3727c5ac
	v_fmamk_f32 v40, v40, 0x3a800000, v41
	v_cmp_gt_f32_e32 vcc, s37, v40
	v_mul_f32_e32 v41, 0x4b800000, v40
	s_nop 0
	v_cndmask_b32_e32 v40, v40, v41, vcc
	v_rsq_f32_e32 v40, v40
	s_nop 0
	v_mul_f32_e32 v41, 0x45800000, v40
	v_cndmask_b32_e32 v40, v40, v41, vcc
	v_pk_mul_f32 v[34:35], v[34:35], v[40:41] op_sel_hi:[1,0]
	v_pk_mul_f32 v[36:37], v[36:37], v[40:41] op_sel_hi:[1,0]
	v_pk_fma_f32 v[34:35], v[2:3], v[34:35], v[10:11]
	v_pk_fma_f32 v[36:37], v[4:5], v[36:37], v[12:13]
	s_and_saveexec_b64 s[54:55], s[40:41]
	s_cbranch_execz .LBB0_51
	global_store_dwordx4 v[52:53], v[34:37], off
